# fox_block loop: pair-path LDS fragment reads rolled through 5 free quads (reads issued 4 MFMAs ahead, counted lgkmcnt); accumulator copy round trip removed from pair and idle steps
# speedup vs baseline: 1.0265x; 1.0144x over previous
; #define NEG_INF (-__builtin_inff())
; DI float xhalf_max(float v) { const auto r = __builtin_amdgcn_permlane32_swap(__float_as_uint(v), __float_as_uint(v), false, false); return fmaxf(__uint_as_float(r[0]), __uint_as_float(r[1])); }
; #define LAS __attribute__((address_space(3)))
; DI int crow(int i, int g) { return (i & 3) + 8 * (i >> 2) + 4 * g; }
; DI void softmax_step_lds(AttnState& st, float (&sc)[16], const LAS unsigned char* stv, const LaneKV& L) {
;   float mx = st.m;
; #pragma unroll
;   for (int i = 0; i < 16; ++i) mx = fmaxf(mx, sc[i]);
;   mx = xhalf_max(mx);
;   const float ms = (mx == NEG_INF) ? 0.f : mx;
;   if (__builtin_amdgcn_ballot_w64(mx > st.m) != 0ull) {
; DI void fox_block(const Params& p, int e, int bh, int j) {
;     ...
;     const int ka = 2 * i, kb = ka + 1;
;     const LAS unsigned char* sg = lds + (i & 1) * 2 * AT_STAGE;
;     if (kb <= tile) {
;       f32x16 acca = score_tile_lds(qf, sg, L); __builtin_amdgcn_sched_barrier(0); f32x16 accb = score_tile_lds(qf, sg + AT_STAGE, L); __builtin_amdgcn_sched_barrier(0);
;       float sa[16], sb[16];
; #pragma unroll
;       for (int q = 0; q < 4; ++q) {
;         const f32x4 ca = *(const LAS f32x4*)(c2l + ka * 32 + 8 * q + 4 * g), cb = *(const LAS f32x4*)(c2l + kb * 32 + 8 * q + 4 * g);
; #pragma unroll
;         for (int e2 = 0; e2 < 4; ++e2) { sa[q * 4 + e2] = acca[q * 4 + e2] - ca[e2]; sb[q * 4 + e2] = accb[q * 4 + e2] - cb[e2]; }
;       }
;       if (kb == tile) {
; #pragma unroll
;         for (int q = 0; q < 16; ++q) sb[q] = (crow(q, g) <= lr) ? sb[q] : NEG_INF;
;       }
;       softmax_step2_lds(st, sa, sb, sg + 8192, sg + AT_STAGE + 8192, L);
;     } else if (ka <= tile) {
;       f32x16 acc = score_tile_lds(qf, sg, L);
;       float sc[16];
; #pragma unroll
;       for (int q = 0; q < 4; ++q) {
;         const f32x4 cs = *(const LAS f32x4*)(c2l + ka * 32 + 8 * q + 4 * g);
; #pragma unroll
;         for (int e2 = 0; e2 < 4; ++e2) sc[q * 4 + e2] = acc[q * 4 + e2] - cs[e2];
;       }
; #pragma unroll
;       for (int q = 0; q < 16; ++q) sc[q] = (crow(q, g) <= lr) ? sc[q] : NEG_INF;
;       softmax_step_lds(st, sc, sg + 8192, L);
.LBB0_323:
	s_and_b32 s8, s13, 0x8000
	s_add_i32 s16, s8, 0
	s_cmp_ge_i32 s15, s10
	s_mov_b64 s[8:9], -1
	s_cbranch_scc0 .LBB0_329
	s_cmp_gt_i32 s15, s10
	s_cbranch_scc1 .Lfox_idle
	v_mov_b64_e32 v[142:143], v[30:31]
	v_mov_b64_e32 v[126:127], v[46:47]
	v_mov_b64_e32 v[110:111], v[62:63]
	v_mov_b64_e32 v[94:95], v[78:79]
	s_cmp_gt_i32 s15, s10
	v_mov_b64_e32 v[140:141], v[28:29]
	v_mov_b64_e32 v[138:139], v[26:27]
	v_mov_b64_e32 v[136:137], v[24:25]
	v_mov_b64_e32 v[134:135], v[22:23]
	v_mov_b64_e32 v[132:133], v[20:21]
	v_mov_b64_e32 v[130:131], v[18:19]
	v_mov_b64_e32 v[128:129], v[16:17]
	v_mov_b64_e32 v[124:125], v[44:45]
	v_mov_b64_e32 v[122:123], v[42:43]
	v_mov_b64_e32 v[120:121], v[40:41]
	v_mov_b64_e32 v[118:119], v[38:39]
	v_mov_b64_e32 v[116:117], v[36:37]
	v_mov_b64_e32 v[114:115], v[34:35]
	v_mov_b64_e32 v[112:113], v[32:33]
	v_mov_b64_e32 v[108:109], v[60:61]
	v_mov_b64_e32 v[106:107], v[58:59]
	v_mov_b64_e32 v[104:105], v[56:57]
	v_mov_b64_e32 v[102:103], v[54:55]
	v_mov_b64_e32 v[100:101], v[52:53]
	v_mov_b64_e32 v[98:99], v[50:51]
	v_mov_b64_e32 v[96:97], v[48:49]
	v_mov_b64_e32 v[92:93], v[76:77]
	v_mov_b64_e32 v[90:91], v[74:75]
	v_mov_b64_e32 v[88:89], v[72:73]
	v_mov_b64_e32 v[86:87], v[70:71]
	v_mov_b64_e32 v[84:85], v[68:69]
	v_mov_b64_e32 v[82:83], v[66:67]
	v_mov_b64_e32 v[80:81], v[64:65]
	v_mov_b32_e32 v10, v223
	v_mov_b32_e32 v11, v222
	s_cbranch_scc1 .LBB0_328
	v_add_u32_e32 v0, s16, v211
	v_add_u32_e32 v2, v0, v213
	ds_read_b128 v[2:5], v2
	s_mov_b32 s8, 0xff800000
	v_mov_b64_e32 v[110:111], v[62:63]
	v_mov_b64_e32 v[126:127], v[46:47]
	v_mov_b64_e32 v[142:143], v[30:31]
	v_mov_b32_e32 v227, v222
	v_mov_b64_e32 v[108:109], v[60:61]
	v_mov_b64_e32 v[106:107], v[58:59]
	v_mov_b64_e32 v[104:105], v[56:57]
	s_waitcnt lgkmcnt(0)
	v_mfma_f32_32x32x16_bf16 v[80:95], v[2:5], v[172:175], 0
	v_add_u32_e32 v2, v0, v214
	ds_read_b128 v[2:5], v2
	v_mov_b64_e32 v[102:103], v[54:55]
	v_mov_b64_e32 v[100:101], v[52:53]
	v_mov_b64_e32 v[98:99], v[50:51]
	v_mov_b64_e32 v[96:97], v[48:49]
	v_mov_b64_e32 v[124:125], v[44:45]
	v_mov_b64_e32 v[122:123], v[42:43]
	v_mov_b64_e32 v[120:121], v[40:41]
	s_waitcnt lgkmcnt(0)
	v_mfma_f32_32x32x16_bf16 v[80:95], v[2:5], v[168:171], v[80:95]
	v_add_u32_e32 v2, v0, v215
	ds_read_b128 v[2:5], v2
	v_mov_b64_e32 v[118:119], v[38:39]
	v_mov_b64_e32 v[116:117], v[36:37]
	v_mov_b64_e32 v[114:115], v[34:35]
	v_mov_b64_e32 v[112:113], v[32:33]
	v_mov_b64_e32 v[140:141], v[28:29]
	v_mov_b64_e32 v[138:139], v[26:27]
	s_waitcnt lgkmcnt(0)
	v_mfma_f32_32x32x16_bf16 v[80:95], v[2:5], v[164:167], v[80:95]
	v_add_u32_e32 v2, v0, v216
	ds_read_b128 v[2:5], v2
	v_mov_b64_e32 v[136:137], v[24:25]
	v_mov_b64_e32 v[134:135], v[22:23]
	v_mov_b64_e32 v[132:133], v[20:21]
	v_mov_b64_e32 v[130:131], v[18:19]
	v_mov_b64_e32 v[128:129], v[16:17]
	s_waitcnt lgkmcnt(0)
	v_mfma_f32_32x32x16_bf16 v[80:95], v[2:5], v[160:163], v[80:95]
	v_add_u32_e32 v2, v0, v217
	ds_read_b128 v[2:5], v2
	s_waitcnt lgkmcnt(0)
	v_mfma_f32_32x32x16_bf16 v[80:95], v[2:5], v[156:159], v[80:95]
	v_add_u32_e32 v2, v0, v218
	ds_read_b128 v[2:5], v2
	s_waitcnt lgkmcnt(0)
	v_mfma_f32_32x32x16_bf16 v[80:95], v[2:5], v[152:155], v[80:95]
	v_add_u32_e32 v2, v0, v219
	ds_read_b128 v[2:5], v2
	v_add_u32_e32 v0, v0, v220
	s_waitcnt lgkmcnt(0)
	v_mfma_f32_32x32x16_bf16 v[80:95], v[2:5], v[148:151], v[80:95]
	ds_read_b128 v[2:5], v0
	v_add_u32_e32 v0, s14, v221
	s_waitcnt lgkmcnt(0)
	v_mfma_f32_32x32x16_bf16 v[80:95], v[2:5], v[144:147], v[80:95]
	v_add_u32_e32 v2, 0x10000, v0
	ds_read_b128 v[2:5], v2
	s_waitcnt lgkmcnt(0)
	s_nop 8
	v_sub_f32_e32 v8, v82, v4
	v_add_u32_e32 v4, 0x10020, v0
	v_sub_f32_e32 v9, v83, v5
	ds_read_b128 v[4:7], v4
	v_sub_f32_e32 v3, v81, v3
	v_sub_f32_e32 v2, v80, v2
	v_cndmask_b32_e64 v226, v2, v248, s[38:39]
	v_cndmask_b32_e64 v225, v248, v3, s[40:41]
	s_waitcnt lgkmcnt(0)
	v_sub_f32_e32 v10, v84, v4
	v_add_u32_e32 v4, 0x10040, v0
	v_sub_f32_e32 v11, v85, v5
	v_sub_f32_e32 v12, v86, v6
	v_sub_f32_e32 v81, v87, v7
	ds_read_b128 v[4:7], v4
	v_add_u32_e32 v0, 0x10060, v0
	v_cndmask_b32_e64 v224, v8, v248, s[42:43]
	v_cndmask_b32_e64 v15, v9, v248, s[44:45]
	v_cndmask_b32_e64 v14, v10, v248, s[46:47]
	s_waitcnt lgkmcnt(0)
	v_sub_f32_e32 v82, v88, v4
	v_sub_f32_e32 v83, v89, v5
	v_sub_f32_e32 v84, v90, v6
	v_sub_f32_e32 v85, v91, v7
	ds_read_b128 v[4:7], v0
	v_cndmask_b32_e64 v13, v11, v248, s[48:49]
	v_cndmask_b32_e64 v12, v12, v248, s[50:51]
	v_cndmask_b32_e64 v11, v81, v248, s[52:53]
	v_cndmask_b32_e64 v9, v82, v248, s[54:55]
	s_waitcnt lgkmcnt(0)
	v_sub_f32_e32 v0, v92, v4
	v_sub_f32_e32 v4, v93, v5
	v_cndmask_b32_e64 v3, v4, v248, s[64:65]
	v_max3_f32 v4, v223, v226, v225
	v_max3_f32 v4, v4, v224, v15
	v_max3_f32 v4, v4, v14, v13
	v_cndmask_b32_e64 v8, v83, v248, s[56:57]
	v_max3_f32 v4, v4, v12, v11
	v_sub_f32_e32 v86, v94, v6
	v_sub_f32_e32 v87, v95, v7
	v_cndmask_b32_e64 v7, v84, v248, s[58:59]
	v_cndmask_b32_e64 v6, v85, v248, s[60:61]
	v_max3_f32 v4, v4, v9, v8
	v_cndmask_b32_e64 v5, v0, v248, s[62:63]
	v_max3_f32 v4, v4, v7, v6
	v_cndmask_b32_e64 v2, v86, v248, s[66:67]
	v_cndmask_b32_e64 v0, v87, v248, s[68:69]
	v_max3_f32 v4, v4, v5, v3
	v_max3_f32 v4, v4, v2, v0
	v_mov_b32_e32 v10, v4
	s_nop 1
	v_permlane32_swap_b32_e32 v4, v10
	v_max_f32_e32 v10, v10, v10
	v_max_f32_e32 v4, v4, v4
	v_max_f32_e32 v10, v4, v10
	v_cmp_neq_f32_e32 vcc, s8, v10
	v_mov_b64_e32 v[94:95], v[78:79]
	v_mov_b64_e32 v[92:93], v[76:77]
	v_cndmask_b32_e32 v4, 0, v10, vcc
	v_cmp_gt_f32_e32 vcc, v10, v223
	v_mov_b64_e32 v[90:91], v[74:75]
	v_mov_b64_e32 v[88:89], v[72:73]
	v_mov_b64_e32 v[86:87], v[70:71]
	v_mov_b64_e32 v[84:85], v[68:69]
	v_mov_b64_e32 v[82:83], v[66:67]
	v_mov_b64_e32 v[80:81], v[64:65]
	s_cbranch_vccz .LBB0_327
; DI float fexp2(float x) { return __builtin_amdgcn_exp2f(x); }
; DI void softmax_step_lds(AttnState& st, float (&sc)[16], const LAS unsigned char* stv, const LaneKV& L) {
;     ...
;     const float alpha = fexp2(st.m - ms);
;     st.l *= alpha;
; #pragma unroll
;     for (int vt = 0; vt < 4; ++vt)
; #pragma unroll
;       for (int i = 0; i < 16; ++i) st.o[vt][i] *= alpha;
	v_sub_f32_e32 v80, v223, v4
	v_exp_f32_e32 v80, v80
	s_nop 0
	v_mul_f32_e32 v227, v222, v80
	v_pk_mul_f32 v[142:143], v[30:31], v[80:81] op_sel_hi:[1,0]
	v_pk_mul_f32 v[140:141], v[28:29], v[80:81] op_sel_hi:[1,0]
	v_pk_mul_f32 v[138:139], v[26:27], v[80:81] op_sel_hi:[1,0]
	v_pk_mul_f32 v[136:137], v[24:25], v[80:81] op_sel_hi:[1,0]
	v_pk_mul_f32 v[134:135], v[22:23], v[80:81] op_sel_hi:[1,0]
	v_pk_mul_f32 v[132:133], v[20:21], v[80:81] op_sel_hi:[1,0]
	v_pk_mul_f32 v[130:131], v[18:19], v[80:81] op_sel_hi:[1,0]
	v_pk_mul_f32 v[128:129], v[16:17], v[80:81] op_sel_hi:[1,0]
	v_pk_mul_f32 v[126:127], v[46:47], v[80:81] op_sel_hi:[1,0]
	v_pk_mul_f32 v[124:125], v[44:45], v[80:81] op_sel_hi:[1,0]
	v_pk_mul_f32 v[122:123], v[42:43], v[80:81] op_sel_hi:[1,0]
	v_pk_mul_f32 v[120:121], v[40:41], v[80:81] op_sel_hi:[1,0]
	v_pk_mul_f32 v[118:119], v[38:39], v[80:81] op_sel_hi:[1,0]
	v_pk_mul_f32 v[116:117], v[36:37], v[80:81] op_sel_hi:[1,0]
	v_pk_mul_f32 v[114:115], v[34:35], v[80:81] op_sel_hi:[1,0]
	v_pk_mul_f32 v[112:113], v[32:33], v[80:81] op_sel_hi:[1,0]
	v_pk_mul_f32 v[110:111], v[62:63], v[80:81] op_sel_hi:[1,0]
	v_pk_mul_f32 v[108:109], v[60:61], v[80:81] op_sel_hi:[1,0]
	v_pk_mul_f32 v[106:107], v[58:59], v[80:81] op_sel_hi:[1,0]
	v_pk_mul_f32 v[104:105], v[56:57], v[80:81] op_sel_hi:[1,0]
	v_pk_mul_f32 v[102:103], v[54:55], v[80:81] op_sel_hi:[1,0]
	v_pk_mul_f32 v[100:101], v[52:53], v[80:81] op_sel_hi:[1,0]
	v_pk_mul_f32 v[98:99], v[50:51], v[80:81] op_sel_hi:[1,0]
	v_pk_mul_f32 v[96:97], v[48:49], v[80:81] op_sel_hi:[1,0]
	v_pk_mul_f32 v[94:95], v[78:79], v[80:81] op_sel_hi:[1,0]
	v_pk_mul_f32 v[92:93], v[76:77], v[80:81] op_sel_hi:[1,0]
	v_pk_mul_f32 v[90:91], v[74:75], v[80:81] op_sel_hi:[1,0]
	v_pk_mul_f32 v[88:89], v[72:73], v[80:81] op_sel_hi:[1,0]
	v_pk_mul_f32 v[86:87], v[70:71], v[80:81] op_sel_hi:[1,0]
	v_pk_mul_f32 v[84:85], v[68:69], v[80:81] op_sel_hi:[1,0]
	v_pk_mul_f32 v[82:83], v[66:67], v[80:81] op_sel_hi:[1,0]
	v_pk_mul_f32 v[80:81], v[64:65], v[80:81] op_sel_hi:[1,0]

; #define NEG_INF (-__builtin_inff())
; DI f32x16 mfma32(bf16x8 a, bf16x8 b, f32x16 c) { return __builtin_amdgcn_mfma_f32_32x32x16_bf16(a, b, c, 0, 0, 0); }
; DI f32x16 zero16() { f32x16 z; for (int i = 0; i < 16; ++i) z[i] = 0.f; return z; }
; #define LAS __attribute__((address_space(3)))
; DI int crow(int i, int g) { return (i & 3) + 8 * (i >> 2) + 4 * g; }
; DI f32x16 score_tile_lds(const bf16x8 (&qf)[8], const LAS unsigned char* st, const LaneKV& L) {
;   f32x16 acc = zero16();
; #pragma unroll
;   for (int ks = 0; ks < 8; ++ks) { const bf16x8 a = *(const LAS bf16x8*)(st + L.kx + (((unsigned)ks ^ L.xh) << 5)); acc = mfma32(a, qf[ks], acc); }
;   return acc;
; DI void fox_block(const Params& p, int e, int bh, int j) {
;     ...
;     if (kb <= tile) {
;       f32x16 acca = score_tile_lds(qf, sg, L); __builtin_amdgcn_sched_barrier(0); f32x16 accb = score_tile_lds(qf, sg + AT_STAGE, L); __builtin_amdgcn_sched_barrier(0);
;       float sa[16], sb[16];
; #pragma unroll
;       for (int q = 0; q < 4; ++q) {
;         const f32x4 ca = *(const LAS f32x4*)(c2l + ka * 32 + 8 * q + 4 * g), cb = *(const LAS f32x4*)(c2l + kb * 32 + 8 * q + 4 * g);
; #pragma unroll
;         for (int e2 = 0; e2 < 4; ++e2) { sa[q * 4 + e2] = acca[q * 4 + e2] - ca[e2]; sb[q * 4 + e2] = accb[q * 4 + e2] - cb[e2]; }
;       }
;       if (kb == tile) {
; #pragma unroll
;         for (int q = 0; q < 16; ++q) sb[q] = (crow(q, g) <= lr) ? sb[q] : NEG_INF;
;       }
.LBB0_329:
	s_andn2_b64 vcc, exec, s[8:9]
	s_cbranch_vccnz .LBB0_335
	v_add_u32_e32 v0, s16, v211
	v_add_u32_e32 v6, v0, v213
	v_add_u32_e32 v7, v0, v214
	v_add_u32_e32 v8, v0, v215
	v_add_u32_e32 v9, v0, v216
	v_add_u32_e32 v10, v0, v217
	v_add_u32_e32 v11, v0, v218
	v_add_u32_e32 v12, v0, v219
	v_add_u32_e32 v0, v0, v220
	ds_read_b128 v[228:231], v6
	ds_read_b128 v[232:235], v7
	ds_read_b128 v[236:239], v8
	ds_read_b128 v[240:243], v9
	ds_read_b128 v[244:247], v10
	s_waitcnt lgkmcnt(4)
	v_mfma_f32_32x32x16_bf16 v[80:95], v[228:231], v[172:175], 0
	ds_read_b128 v[228:231], v11
	s_waitcnt lgkmcnt(4)
	v_mfma_f32_32x32x16_bf16 v[80:95], v[232:235], v[168:171], v[80:95]
	ds_read_b128 v[232:235], v12
	s_waitcnt lgkmcnt(4)
	v_mfma_f32_32x32x16_bf16 v[80:95], v[236:239], v[164:167], v[80:95]
	ds_read_b128 v[236:239], v0
	s_waitcnt lgkmcnt(4)
	v_mfma_f32_32x32x16_bf16 v[80:95], v[240:243], v[160:163], v[80:95]
	ds_read_b128 v[240:243], v6 offset:16384
	s_waitcnt lgkmcnt(4)
	v_mfma_f32_32x32x16_bf16 v[80:95], v[244:247], v[156:159], v[80:95]
	ds_read_b128 v[244:247], v7 offset:16384
	s_waitcnt lgkmcnt(4)
	v_mfma_f32_32x32x16_bf16 v[80:95], v[228:231], v[152:155], v[80:95]
	ds_read_b128 v[228:231], v8 offset:16384
	s_waitcnt lgkmcnt(4)
	v_mfma_f32_32x32x16_bf16 v[80:95], v[232:235], v[148:151], v[80:95]
	ds_read_b128 v[232:235], v9 offset:16384
	s_waitcnt lgkmcnt(4)
	v_mfma_f32_32x32x16_bf16 v[80:95], v[236:239], v[144:147], v[80:95]
	ds_read_b128 v[236:239], v10 offset:16384
	s_waitcnt lgkmcnt(4)
	v_mfma_f32_32x32x16_bf16 v[96:111], v[240:243], v[172:175], 0
	ds_read_b128 v[240:243], v11 offset:16384
	s_waitcnt lgkmcnt(4)
	v_mfma_f32_32x32x16_bf16 v[96:111], v[244:247], v[168:171], v[96:111]
	ds_read_b128 v[244:247], v12 offset:16384
	s_waitcnt lgkmcnt(4)
	v_mfma_f32_32x32x16_bf16 v[96:111], v[228:231], v[164:167], v[96:111]
	ds_read_b128 v[228:231], v0 offset:16384
	s_waitcnt lgkmcnt(4)
	v_mfma_f32_32x32x16_bf16 v[96:111], v[232:235], v[160:163], v[96:111]
	s_waitcnt lgkmcnt(3)
	v_mfma_f32_32x32x16_bf16 v[96:111], v[236:239], v[156:159], v[96:111]
	s_waitcnt lgkmcnt(2)
	v_mfma_f32_32x32x16_bf16 v[96:111], v[240:243], v[152:155], v[96:111]
	s_waitcnt lgkmcnt(1)
	v_mfma_f32_32x32x16_bf16 v[96:111], v[244:247], v[148:151], v[96:111]
	s_waitcnt lgkmcnt(0)
	v_mfma_f32_32x32x16_bf16 v[96:111], v[228:231], v[144:147], v[96:111]
	v_add_u32_e32 v0, s14, v221
	v_add_u32_e32 v2, 0x10000, v0
	v_add_u32_e32 v6, 0x10080, v0
	ds_read_b128 v[2:5], v2
	ds_read_b128 v[6:9], v6
	v_add_u32_e32 v10, 0x100a0, v0
	ds_read_b128 v[10:13], v10
	s_cmp_lg_u32 s12, s15
	s_waitcnt lgkmcnt(0)
	s_nop 2
	v_pk_add_f32 v[112:113], v[96:97], v[6:7] neg_lo:[0,1] neg_hi:[0,1]
	v_add_u32_e32 v96, 0x100c0, v0
	v_pk_add_f32 v[14:15], v[98:99], v[8:9] neg_lo:[0,1] neg_hi:[0,1]
	ds_read_b128 v[96:99], v96
	v_add_u32_e32 v6, 0x10020, v0
	v_pk_add_f32 v[114:115], v[100:101], v[10:11] neg_lo:[0,1] neg_hi:[0,1]
	v_add_u32_e32 v10, 0x10040, v0
	ds_read_b128 v[6:9], v6
	s_waitcnt lgkmcnt(0)
	v_pk_add_f32 v[104:105], v[104:105], v[96:97] neg_lo:[0,1] neg_hi:[0,1]
	v_add_u32_e32 v96, 0x10060, v0
	v_add_u32_e32 v0, 0x100e0, v0
	ds_read_b128 v[116:119], v0
	v_pk_add_f32 v[102:103], v[102:103], v[12:13] neg_lo:[0,1] neg_hi:[0,1]
	ds_read_b128 v[10:13], v10
	v_pk_add_f32 v[100:101], v[106:107], v[98:99] neg_lo:[0,1] neg_hi:[0,1]
	ds_read_b128 v[96:99], v96
	s_waitcnt lgkmcnt(0)
	v_pk_add_f32 v[108:109], v[108:109], v[116:117] neg_lo:[0,1] neg_hi:[0,1]
	v_pk_add_f32 v[106:107], v[110:111], v[118:119] neg_lo:[0,1] neg_hi:[0,1]
	s_cbranch_scc1 .LBB0_332
	v_cndmask_b32_e64 v112, v112, v248, s[38:39]
	v_cndmask_b32_e64 v113, v248, v113, s[40:41]
	v_cndmask_b32_e64 v14, v14, v248, s[42:43]
	v_cndmask_b32_e64 v15, v15, v248, s[44:45]
	v_cndmask_b32_e64 v114, v114, v248, s[46:47]
	v_cndmask_b32_e64 v115, v115, v248, s[48:49]
	v_cndmask_b32_e64 v102, v102, v248, s[50:51]
	v_cndmask_b32_e64 v103, v103, v248, s[52:53]
	v_cndmask_b32_e64 v104, v104, v248, s[54:55]
	v_cndmask_b32_e64 v105, v105, v248, s[56:57]
	v_cndmask_b32_e64 v100, v100, v248, s[58:59]
	v_cndmask_b32_e64 v101, v101, v248, s[60:61]
	v_cndmask_b32_e64 v108, v108, v248, s[62:63]
	v_cndmask_b32_e64 v109, v109, v248, s[64:65]
	v_cndmask_b32_e64 v106, v106, v248, s[66:67]
	v_cndmask_b32_e64 v107, v107, v248, s[68:69]

; DI float fexp2(float x) { return __builtin_amdgcn_exp2f(x); }
; DI f32x16 mfma32(bf16x8 a, bf16x8 b, f32x16 c) { return __builtin_amdgcn_mfma_f32_32x32x16_bf16(a, b, c, 0, 0, 0); }
; #define LAS __attribute__((address_space(3)))
; DI bf16x8 pack8(const float* p) { u32x4 o; o.x = pk2h(p[0], p[1]); o.y = pk2h(p[2], p[3]); o.z = pk2h(p[4], p[5]); o.w = pk2h(p[6], p[7]); return __builtin_bit_cast(bf16x8, o); }
; DI void pv_tile_lds(f32x16 (&o)[4], const bf16x8 (&pf)[2], const LAS unsigned char* stv, const LaneKV& L) {
; #pragma unroll
;   for (int vt = 0; vt < 4; ++vt) {
; #pragma unroll
;     for (int s2 = 0; s2 < 2; ++s2) {
;       const s16x4 lo = *(const LAS s16x4*)(stv + vt * 2048 + L.vrow + L.vo[2 * s2]), hi = *(const LAS s16x4*)(stv + vt * 2048 + L.vrow + L.vo[2 * s2 + 1]);
;       const bf16x8 a = __builtin_shufflevector(lo, hi, 0, 1, 2, 3, 4, 5, 6, 7);
;       o[vt] = mfma32(a, pf[s2], o[vt]);
;     }
;   }
; }
; DI void softmax_step2_lds(AttnState& st, float (&sa)[16], float (&sb)[16], const LAS unsigned char* stva, const LAS unsigned char* stvb, const LaneKV& L) {
;     ...
;   float ps = 0.f;
; #pragma unroll
;   for (int i = 0; i < 16; ++i) { sa[i] = fexp2(sa[i] - ms); sb[i] = fexp2(sb[i] - ms); ps += sa[i] + sb[i]; }
;   st.l += ps;
;   bf16x8 pfa[2], pfb[2]; pfa[0] = pack8(sa); pfa[1] = pack8(sa + 8); pfb[0] = pack8(sb); pfb[1] = pack8(sb + 8);
;   __builtin_amdgcn_sched_barrier(0);
;   pv_tile_lds(st.o, pfa, stva, L);
;   __builtin_amdgcn_sched_barrier(0);
;   pv_tile_lds(st.o, pfb, stvb, L);
;   __builtin_amdgcn_sched_barrier(0);
; }
.LBB0_334:
	v_sub_f32_e32 v12, v116, v11
	v_exp_f32_e32 v116, v12
	v_sub_f32_e32 v12, v112, v11
	v_sub_f32_e32 v0, v0, v11
	v_exp_f32_e32 v112, v12
	v_exp_f32_e32 v12, v0
	v_sub_f32_e32 v0, v113, v11
	v_exp_f32_e32 v0, v0
	v_add_f32_e32 v13, v116, v112
	v_sub_f32_e32 v14, v14, v11
	v_sub_f32_e32 v15, v15, v11
	v_pk_add_f32 v[84:85], v[12:13], v[0:1]
	v_sub_f32_e32 v13, v111, v11
	v_pk_add_f32 v[84:85], v[84:85], v[84:85] op_sel_hi:[0,1]
	v_exp_f32_e32 v13, v13
	v_exp_f32_e32 v111, v14
	v_sub_f32_e32 v14, v110, v11
	v_exp_f32_e32 v14, v14
	v_exp_f32_e32 v84, v15
	v_add_f32_e32 v15, v13, v111
	v_sub_f32_e32 v82, v82, v11
	v_exp_f32_e32 v82, v82
	v_pk_add_f32 v[86:87], v[14:15], v[84:85]
	v_sub_f32_e32 v15, v83, v11
	v_sub_f32_e32 v83, v114, v11
	v_pk_add_f32 v[86:87], v[86:87], v[86:87] op_sel_hi:[0,1]
	v_exp_f32_e32 v15, v15
	v_exp_f32_e32 v85, v83
	v_sub_f32_e32 v83, v115, v11
	v_exp_f32_e32 v86, v83
	v_sub_f32_e32 v81, v81, v11
	v_add_f32_e32 v83, v15, v85
	v_sub_f32_e32 v80, v80, v11
	v_pk_add_f32 v[88:89], v[82:83], v[86:87]
	v_exp_f32_e32 v83, v81
	v_sub_f32_e32 v81, v102, v11
	v_pk_add_f32 v[88:89], v[88:89], v[88:89] op_sel_hi:[0,1]
	v_exp_f32_e32 v87, v81
	v_sub_f32_e32 v81, v103, v11
	v_exp_f32_e32 v80, v80
	v_exp_f32_e32 v88, v81
	v_add_f32_e32 v81, v83, v87
	v_sub_f32_e32 v9, v9, v11
	v_sub_f32_e32 v8, v8, v11
	v_pk_add_f32 v[90:91], v[80:81], v[88:89]
	v_exp_f32_e32 v81, v9
	v_sub_f32_e32 v9, v104, v11
	v_pk_add_f32 v[90:91], v[90:91], v[90:91] op_sel_hi:[0,1]
	v_exp_f32_e32 v89, v9
	v_sub_f32_e32 v9, v105, v11
	v_exp_f32_e32 v8, v8
	v_exp_f32_e32 v90, v9
	v_add_f32_e32 v9, v81, v89
	v_sub_f32_e32 v7, v7, v11
	v_sub_f32_e32 v6, v6, v11
	v_pk_add_f32 v[92:93], v[8:9], v[90:91]
	v_exp_f32_e32 v9, v7
	v_sub_f32_e32 v7, v100, v11
	v_pk_add_f32 v[92:93], v[92:93], v[92:93] op_sel_hi:[0,1]
	v_exp_f32_e32 v91, v7
	v_sub_f32_e32 v7, v101, v11
	v_exp_f32_e32 v6, v6
	v_exp_f32_e32 v92, v7
	v_add_f32_e32 v7, v9, v91
	v_sub_f32_e32 v5, v5, v11
	v_sub_f32_e32 v4, v4, v11
	v_pk_add_f32 v[94:95], v[6:7], v[92:93]
	v_exp_f32_e32 v7, v5
	v_sub_f32_e32 v5, v108, v11
	v_pk_add_f32 v[94:95], v[94:95], v[94:95] op_sel_hi:[0,1]
	v_exp_f32_e32 v93, v5
	v_sub_f32_e32 v5, v109, v11
	v_exp_f32_e32 v4, v4
	v_exp_f32_e32 v94, v5
	v_add_f32_e32 v5, v7, v93
	v_sub_f32_e32 v3, v3, v11
	v_sub_f32_e32 v2, v2, v11
	v_pk_add_f32 v[96:97], v[4:5], v[94:95]
	v_exp_f32_e32 v5, v3
	v_sub_f32_e32 v3, v106, v11
	v_pk_add_f32 v[96:97], v[96:97], v[96:97] op_sel_hi:[0,1]
	v_exp_f32_e32 v95, v3
	v_sub_f32_e32 v3, v107, v11
	v_exp_f32_e32 v2, v2
	v_exp_f32_e32 v96, v3
	v_add_f32_e32 v3, v5, v95
	v_cvt_pk_bf16_f32 v13, v13, v14
	v_cvt_pk_bf16_f32 v14, v15, v82
	v_pk_add_f32 v[98:99], v[2:3], v[96:97]
	v_cvt_pk_bf16_f32 v15, v83, v80
	v_add_f32_e32 v3, v98, v99
	v_add_f32_e32 v11, v3, v222
	v_cvt_pk_bf16_f32 v80, v81, v8
	v_cvt_pk_bf16_f32 v81, v9, v6
	v_cvt_pk_bf16_f32 v82, v7, v4
	v_cvt_pk_bf16_f32 v83, v5, v2
	v_cvt_pk_bf16_f32 v12, v116, v12
	v_cvt_pk_bf16_f32 v6, v112, v0
	v_cvt_pk_bf16_f32 v7, v111, v84
	v_cvt_pk_bf16_f32 v8, v85, v86
	v_cvt_pk_bf16_f32 v9, v87, v88
	v_cvt_pk_bf16_f32 v2, v89, v90
	v_cvt_pk_bf16_f32 v3, v91, v92
	v_cvt_pk_bf16_f32 v4, v93, v94
	v_cvt_pk_bf16_f32 v5, v95, v96
	v_add_u32_e32 v0, s16, v183
	v_add_u32_e32 v104, v0, v207
	v_add_u32_e32 v105, v0, v208
	v_add_u32_e32 v106, v0, v209
	v_add_u32_e32 v0, v0, v210
	ds_read_b64 v[228:229], v104 offset:8192
	ds_read_b64 v[230:231], v105 offset:8192
	ds_read_b64 v[232:233], v104 offset:10240
	ds_read_b64 v[234:235], v105 offset:10240
	ds_read_b64 v[236:237], v106 offset:10240
	ds_read_b64 v[238:239], v0 offset:10240
	ds_read_b64 v[240:241], v104 offset:12288
	ds_read_b64 v[242:243], v105 offset:12288
	ds_read_b64 v[244:245], v104 offset:14336
	ds_read_b64 v[246:247], v105 offset:14336
	s_waitcnt lgkmcnt(8)
	v_mfma_f32_32x32x16_bf16 v[16:31], v[228:231], v[12:15], v[16:31]
	ds_read_b64 v[228:229], v106 offset:8192
	ds_read_b64 v[230:231], v0 offset:8192
	s_waitcnt lgkmcnt(8)
	v_mfma_f32_32x32x16_bf16 v[32:47], v[232:235], v[12:15], v[32:47]
	ds_read_b64 v[232:233], v106 offset:12288
	ds_read_b64 v[234:235], v0 offset:12288
	s_waitcnt lgkmcnt(8)
	v_mfma_f32_32x32x16_bf16 v[32:47], v[236:239], v[80:83], v[32:47]
	ds_read_b64 v[236:237], v106 offset:14336
	ds_read_b64 v[238:239], v0 offset:14336
	s_waitcnt lgkmcnt(8)
	v_mfma_f32_32x32x16_bf16 v[48:63], v[240:243], v[12:15], v[48:63]
	ds_read_b64 v[240:241], v104 offset:24576
	ds_read_b64 v[242:243], v105 offset:24576
	s_waitcnt lgkmcnt(8)
	v_mfma_f32_32x32x16_bf16 v[64:79], v[244:247], v[12:15], v[64:79]
	ds_read_b64 v[244:245], v104 offset:26624
	ds_read_b64 v[246:247], v105 offset:26624
	s_waitcnt lgkmcnt(8)
	v_mfma_f32_32x32x16_bf16 v[16:31], v[228:231], v[80:83], v[16:31]
	ds_read_b64 v[228:229], v106 offset:26624
	ds_read_b64 v[230:231], v0 offset:26624
	s_waitcnt lgkmcnt(8)
	v_mfma_f32_32x32x16_bf16 v[48:63], v[232:235], v[80:83], v[48:63]
	ds_read_b64 v[232:233], v104 offset:28672
	ds_read_b64 v[234:235], v105 offset:28672
	s_waitcnt lgkmcnt(8)
	v_mfma_f32_32x32x16_bf16 v[64:79], v[236:239], v[80:83], v[64:79]
	ds_read_b64 v[236:237], v104 offset:30720
	ds_read_b64 v[238:239], v105 offset:30720
	s_waitcnt lgkmcnt(8)
	v_mfma_f32_32x32x16_bf16 v[16:31], v[240:243], v[6:9], v[16:31]
	ds_read_b64 v[240:241], v106 offset:24576
	ds_read_b64 v[242:243], v0 offset:24576
	s_waitcnt lgkmcnt(8)
	v_mfma_f32_32x32x16_bf16 v[32:47], v[244:247], v[6:9], v[32:47]
	ds_read_b64 v[244:245], v106 offset:28672
	ds_read_b64 v[246:247], v0 offset:28672
	s_waitcnt lgkmcnt(8)
	v_mfma_f32_32x32x16_bf16 v[32:47], v[228:231], v[2:5], v[32:47]
	ds_read_b64 v[228:229], v106 offset:30720
	ds_read_b64 v[230:231], v0 offset:30720
	s_waitcnt lgkmcnt(8)
	v_mfma_f32_32x32x16_bf16 v[48:63], v[232:235], v[6:9], v[48:63]
	s_waitcnt lgkmcnt(6)
	v_mfma_f32_32x32x16_bf16 v[64:79], v[236:239], v[6:9], v[64:79]
	s_waitcnt lgkmcnt(4)
	v_mfma_f32_32x32x16_bf16 v[16:31], v[240:243], v[2:5], v[16:31]
	s_waitcnt lgkmcnt(2)
	v_mfma_f32_32x32x16_bf16 v[48:63], v[244:247], v[2:5], v[48:63]
	s_waitcnt lgkmcnt(0)
	v_mfma_f32_32x32x16_bf16 v[64:79], v[228:231], v[2:5], v[64:79]
	s_branch .Lfox_pair_latch

; #define LAS __attribute__((address_space(3)))
; #define AT_WAIT_V(n) asm volatile("s_waitcnt vmcnt(" #n ")" ::: "memory")
; #define AT_BAR() __builtin_amdgcn_s_barrier()
; DI void fox_block(const Params& p, int e, int bh, int j) {
;     ...
;   for (int i = 0; i < nsteps; ++i) {
;     AT_WAIT_V(0);
;     AT_BAR();
;     if (i + 1 < nsteps) {
;       LAS unsigned char* nx = lds + ((i + 1) & 1) * 2 * AT_STAGE;
;       kv_issue(nx, Kb + (size_t)(2 * i + 2) * 4096, VT + (size_t)(2 * i + 2) * 4096, L);
;       kv_issue(nx + AT_STAGE, Kb + (size_t)(2 * i + 3) * 4096, VT + (size_t)(2 * i + 3) * 4096, L);
;     }
.Lfox_pair_latch:
	s_add_i32 s15, s15, 2
	s_addk_i32 s14, 0x100
	s_add_u32 s6, s6, 0x4000
	s_addc_u32 s7, s7, 0
	s_add_i32 s13, s13, 0x8000
	s_add_i32 s11, s11, 1
	s_cmp_lg_u32 s5, s14
	s_cbranch_scc0 .Lfox_exit_pair
	v_mov_b32_e32 v223, v10
	v_mov_b32_e32 v222, v11
	s_branch .LBB0_321
.Lfox_idle:
	s_add_i32 s15, s15, 2
	s_addk_i32 s14, 0x100
	s_add_u32 s6, s6, 0x4000
	s_addc_u32 s7, s7, 0
	s_add_i32 s13, s13, 0x8000
	s_add_i32 s11, s11, 1
	s_cmp_lg_u32 s5, s14
	s_cbranch_scc0 .Lfox_exit_idle
	s_branch .LBB0_321
.Lfox_exit_idle:
	v_mov_b32_e32 v10, v223
	v_mov_b32_e32 v11, v222
.Lfox_exit_pair:
	s_nop 7
	v_mov_b64_e32 v[142:143], v[30:31]
	v_mov_b64_e32 v[126:127], v[46:47]
	v_mov_b64_e32 v[110:111], v[62:63]
	v_mov_b64_e32 v[94:95], v[78:79]
	v_mov_b64_e32 v[140:141], v[28:29]
	v_mov_b64_e32 v[138:139], v[26:27]
	v_mov_b64_e32 v[136:137], v[24:25]
	v_mov_b64_e32 v[134:135], v[22:23]
	v_mov_b64_e32 v[132:133], v[20:21]
	v_mov_b64_e32 v[130:131], v[18:19]
	v_mov_b64_e32 v[128:129], v[16:17]
	v_mov_b64_e32 v[124:125], v[44:45]
	v_mov_b64_e32 v[122:123], v[42:43]
	v_mov_b64_e32 v[120:121], v[40:41]
	v_mov_b64_e32 v[118:119], v[38:39]
	v_mov_b64_e32 v[116:117], v[36:37]
	v_mov_b64_e32 v[114:115], v[34:35]
	v_mov_b64_e32 v[112:113], v[32:33]
	v_mov_b64_e32 v[108:109], v[60:61]
	v_mov_b64_e32 v[106:107], v[58:59]
	v_mov_b64_e32 v[104:105], v[56:57]
	v_mov_b64_e32 v[102:103], v[54:55]
	v_mov_b64_e32 v[100:101], v[52:53]
	v_mov_b64_e32 v[98:99], v[50:51]
	v_mov_b64_e32 v[96:97], v[48:49]
	v_mov_b64_e32 v[92:93], v[76:77]
	v_mov_b64_e32 v[90:91], v[74:75]
	v_mov_b64_e32 v[88:89], v[72:73]
	v_mov_b64_e32 v[86:87], v[70:71]
	v_mov_b64_e32 v[84:85], v[68:69]
	v_mov_b64_e32 v[82:83], v[66:67]
	v_mov_b64_e32 v[80:81], v[64:65]
	s_branch .LBB0_311
